# v29 + nt on DOWN(0) epilogue residual-input loads (cold f32 x)
# baseline (speedup 1.0000x reference)
.LBB0_302:
	s_lshl_b32 s4, s70, 8
	v_mov_b32_e32 v128, v210
	s_add_i32 s4, s4, s58
	v_and_b32_e32 v212, 64, v209
	v_and_or_b32 v194, v128, 15, s4
	s_lshl_b32 s4, s14, 8
	v_bfe_u32 v208, v128, 4, 2
	s_or_b32 s4, s4, s59
	v_lshl_or_b32 v192, v208, 3, s4
	v_ashrrev_i32_e32 v193, 31, v192
	v_ashrrev_i32_e32 v195, 31, v194
	v_lshl_add_u64 v[196:197], v[192:193], 2, s[10:11]
	v_lshlrev_b64 v[128:129], 12, v[194:195]
	v_lshl_add_u64 v[128:129], v[196:197], 0, v[128:129]
	global_load_dwordx4 v[214:217], v[128:129], off nt
	global_load_dwordx4 v[218:221], v[128:129], off offset:16 nt
	global_load_dwordx4 v[222:225], v[128:129], off offset:512 nt
	global_load_dwordx4 v[226:229], v[128:129], off offset:528 nt
	v_or_b32_e32 v202, 16, v194
	v_or_b32_e32 v200, 32, v194
	v_or_b32_e32 v198, 48, v194
	v_ashrrev_i32_e32 v203, 31, v202
	v_ashrrev_i32_e32 v201, 31, v200
	v_ashrrev_i32_e32 v199, 31, v198
	v_lshlrev_b64 v[128:129], 12, v[202:203]
	v_lshlrev_b64 v[130:131], 12, v[200:201]
	v_lshlrev_b64 v[132:133], 12, v[198:199]
	v_lshl_add_u64 v[128:129], v[196:197], 0, v[128:129]
	v_lshl_add_u64 v[130:131], v[196:197], 0, v[130:131]
	v_lshl_add_u64 v[132:133], v[196:197], 0, v[132:133]
	global_load_dwordx4 v[168:171], v[128:129], off offset:16 nt
	global_load_dwordx4 v[172:175], v[128:129], off nt
	global_load_dwordx4 v[160:163], v[128:129], off offset:528 nt
	global_load_dwordx4 v[164:167], v[128:129], off offset:512 nt
	global_load_dwordx4 v[152:155], v[130:131], off offset:16 nt
	global_load_dwordx4 v[156:159], v[130:131], off nt
	global_load_dwordx4 v[144:147], v[130:131], off offset:528 nt
	global_load_dwordx4 v[148:151], v[130:131], off offset:512 nt
	global_load_dwordx4 v[136:139], v[132:133], off offset:16 nt
	global_load_dwordx4 v[140:143], v[132:133], off nt
	s_nop 0
	global_load_dwordx4 v[128:131], v[132:133], off offset:528 nt
	s_nop 0
	global_load_dwordx4 v[132:135], v[132:133], off offset:512 nt
	v_lshlrev_b64 v[230:231], 10, v[194:195]
	v_lshl_add_u64 v[230:231], v[230:231], 0, v[192:193]
	v_xor_b32_e32 v211, 16, v209
	v_add_u32_e32 v212, 64, v212
	v_lshl_add_u64 v[232:233], v[230:231], 2, s[36:37]
	v_xor_b32_e32 v213, 32, v209
	v_cmp_lt_i32_e32 vcc, v211, v212
	v_lshlrev_b64 v[230:231], 1, v[230:231]
	v_lshl_add_u64 v[234:235], s[38:39], 0, v[230:231]
	v_cndmask_b32_e32 v211, v209, v211, vcc
	v_cmp_lt_i32_e32 vcc, v213, v212
	v_lshlrev_b32_e32 v212, 2, v211
	s_lshl_b32 s46, s14, 2
	v_cndmask_b32_e32 v213, v209, v213, vcc
	v_lshlrev_b32_e32 v211, 2, v213
	v_cmp_eq_u32_e32 vcc, 0, v208
	v_or_b32_e32 v230, 0x100, v230
	s_ashr_i32 s47, s46, 31
	s_waitcnt vmcnt(0)
	v_pk_fma_f32 v[126:127], v[126:127], 0.5, v[216:217] op_sel_hi:[1,0,1]
	v_pk_fma_f32 v[124:125], v[124:125], 0.5, v[214:215] op_sel_hi:[1,0,1]
	v_pk_fma_f32 v[122:123], v[122:123], 0.5, v[220:221] op_sel_hi:[1,0,1]
	v_pk_fma_f32 v[120:121], v[120:121], 0.5, v[218:219] op_sel_hi:[1,0,1]
	global_store_dwordx4 v[232:233], v[124:127], off
	global_store_dwordx4 v[232:233], v[120:123], off offset:16
	v_cvt_pk_bf16_f32 v214, v124, v125
	v_cvt_pk_bf16_f32 v215, v126, v127
	v_cvt_pk_bf16_f32 v216, v120, v121
	v_cvt_pk_bf16_f32 v217, v122, v123
	v_mul_f32_e32 v125, v125, v125
	v_mul_f32_e32 v127, v127, v127
	v_mul_f32_e32 v121, v121, v121
	v_mul_f32_e32 v123, v123, v123
	v_fmac_f32_e32 v125, v124, v124
	v_fmac_f32_e32 v127, v126, v126
	v_fmac_f32_e32 v121, v120, v120
	v_fmac_f32_e32 v123, v122, v122
	v_pk_fma_f32 v[118:119], v[118:119], 0.5, v[224:225] op_sel_hi:[1,0,1]
	v_pk_fma_f32 v[116:117], v[116:117], 0.5, v[222:223] op_sel_hi:[1,0,1]
	v_pk_fma_f32 v[114:115], v[114:115], 0.5, v[228:229] op_sel_hi:[1,0,1]
	v_pk_fma_f32 v[112:113], v[112:113], 0.5, v[226:227] op_sel_hi:[1,0,1]
	v_add_f32_e32 v120, v125, v127
	v_add_f32_e32 v121, v121, v123
	v_mul_f32_e32 v208, v117, v117
	v_mul_f32_e32 v213, v119, v119
	v_add_f32_e32 v120, v120, v121
	v_mul_f32_e32 v121, v113, v113
	v_mul_f32_e32 v123, v115, v115
	v_fmac_f32_e32 v208, v116, v116
	v_fmac_f32_e32 v213, v118, v118
	v_fmac_f32_e32 v121, v112, v112
	v_fmac_f32_e32 v123, v114, v114
	v_add_f32_e32 v122, v208, v213
	v_add_f32_e32 v121, v121, v123
	v_add_f32_e32 v121, v122, v121
	v_add_f32_e32 v120, v120, v121
	ds_bpermute_b32 v121, v212, v120
	global_store_dwordx4 v[234:235], v[214:217], off
	global_store_dwordx4 v[232:233], v[116:119], off offset:512
	global_store_dwordx4 v[232:233], v[112:115], off offset:528
	s_nop 0
	v_cvt_pk_bf16_f32 v116, v116, v117
	v_cvt_pk_bf16_f32 v117, v118, v119
	v_cvt_pk_bf16_f32 v118, v112, v113
	s_waitcnt lgkmcnt(0)
	v_add_f32_e32 v112, v120, v121
	ds_bpermute_b32 v113, v211, v112
	v_cvt_pk_bf16_f32 v119, v114, v115
	v_lshl_add_u64 v[114:115], s[38:39], 0, v[230:231]
	global_store_dwordx4 v[114:115], v[116:119], off
	s_and_saveexec_b64 s[48:49], vcc
	s_cbranch_execz .LBB0_304
	v_lshlrev_b64 v[114:115], 6, v[194:195]
	v_lshl_add_u64 v[114:115], s[44:45], 0, v[114:115]
	v_lshl_add_u64 v[114:115], s[46:47], 2, v[114:115]
	s_lshl_b32 s14, s57, 2
	v_lshl_add_u64 v[114:115], v[114:115], 0, s[14:15]
	s_waitcnt lgkmcnt(0)
	v_add_f32_e32 v112, v112, v113
	global_store_dword v[114:115], v112, off

.LBB0_310:
	s_or_b64 exec, exec, s[48:49]
	v_add_u32_e32 v118, 0x80, v194
	v_ashrrev_i32_e32 v119, 31, v118
	s_waitcnt lgkmcnt(0)
	v_lshlrev_b64 v[64:65], 12, v[118:119]
	v_lshl_add_u64 v[64:65], v[196:197], 0, v[64:65]
	global_load_dwordx4 v[120:123], v[64:65], off nt
	global_load_dwordx4 v[124:127], v[64:65], off offset:16 nt
	global_load_dwordx4 v[128:131], v[64:65], off offset:512 nt
	global_load_dwordx4 v[132:135], v[64:65], off offset:528 nt
	v_add_u32_e32 v116, 0x90, v194
	v_add_u32_e32 v114, 0xa0, v194
	v_add_u32_e32 v112, 0xb0, v194
	v_ashrrev_i32_e32 v117, 31, v116
	v_ashrrev_i32_e32 v115, 31, v114
	v_ashrrev_i32_e32 v113, 31, v112
	v_lshlrev_b64 v[64:65], 12, v[116:117]
	v_lshlrev_b64 v[66:67], 12, v[114:115]
	v_lshlrev_b64 v[68:69], 12, v[112:113]
	v_lshl_add_u64 v[64:65], v[196:197], 0, v[64:65]
	v_lshl_add_u64 v[66:67], v[196:197], 0, v[66:67]
	v_lshl_add_u64 v[68:69], v[196:197], 0, v[68:69]
	global_load_dwordx4 v[104:107], v[64:65], off offset:16 nt
	global_load_dwordx4 v[108:111], v[64:65], off nt
	global_load_dwordx4 v[96:99], v[64:65], off offset:528 nt
	global_load_dwordx4 v[100:103], v[64:65], off offset:512 nt
	global_load_dwordx4 v[88:91], v[66:67], off offset:16 nt
	global_load_dwordx4 v[92:95], v[66:67], off nt
	global_load_dwordx4 v[80:83], v[66:67], off offset:528 nt
	global_load_dwordx4 v[84:87], v[66:67], off offset:512 nt
	global_load_dwordx4 v[72:75], v[68:69], off offset:16 nt
	global_load_dwordx4 v[76:79], v[68:69], off nt
	s_nop 0
	global_load_dwordx4 v[64:67], v[68:69], off offset:528 nt
	s_nop 0
	global_load_dwordx4 v[68:71], v[68:69], off offset:512 nt
	v_lshlrev_b64 v[136:137], 10, v[118:119]
	v_lshl_add_u64 v[136:137], v[136:137], 0, v[192:193]
	v_lshl_add_u64 v[138:139], v[136:137], 2, s[36:37]
	v_lshlrev_b64 v[136:137], 1, v[136:137]
	v_lshl_add_u64 v[140:141], s[38:39], 0, v[136:137]
	v_or_b32_e32 v136, 0x100, v136
	s_waitcnt vmcnt(15)
	v_pk_fma_f32 v[62:63], v[62:63], 0.5, v[122:123] op_sel_hi:[1,0,1]
	v_pk_fma_f32 v[60:61], v[60:61], 0.5, v[120:121] op_sel_hi:[1,0,1]
	s_waitcnt vmcnt(14)
	v_pk_fma_f32 v[58:59], v[58:59], 0.5, v[126:127] op_sel_hi:[1,0,1]
	v_pk_fma_f32 v[56:57], v[56:57], 0.5, v[124:125] op_sel_hi:[1,0,1]
	s_waitcnt vmcnt(13)
	v_pk_fma_f32 v[54:55], v[54:55], 0.5, v[130:131] op_sel_hi:[1,0,1]
	v_pk_fma_f32 v[52:53], v[52:53], 0.5, v[128:129] op_sel_hi:[1,0,1]
	s_waitcnt vmcnt(12)
	v_pk_fma_f32 v[50:51], v[50:51], 0.5, v[134:135] op_sel_hi:[1,0,1]
	v_pk_fma_f32 v[48:49], v[48:49], 0.5, v[132:133] op_sel_hi:[1,0,1]
	global_store_dwordx4 v[138:139], v[60:63], off
	global_store_dwordx4 v[138:139], v[56:59], off offset:16
	v_cvt_pk_bf16_f32 v120, v60, v61
	v_cvt_pk_bf16_f32 v121, v62, v63
	v_cvt_pk_bf16_f32 v122, v56, v57
	v_cvt_pk_bf16_f32 v123, v58, v59
	v_mul_f32_e32 v61, v61, v61
	v_mul_f32_e32 v63, v63, v63
	v_mul_f32_e32 v57, v57, v57
	v_mul_f32_e32 v59, v59, v59
	v_mul_f32_e32 v124, v53, v53
	v_mul_f32_e32 v125, v55, v55
	v_mul_f32_e32 v126, v49, v49
	v_mul_f32_e32 v127, v51, v51
	v_fmac_f32_e32 v61, v60, v60
	v_fmac_f32_e32 v63, v62, v62
	v_fmac_f32_e32 v57, v56, v56
	v_fmac_f32_e32 v59, v58, v58
	v_fmac_f32_e32 v124, v52, v52
	v_fmac_f32_e32 v125, v54, v54
	v_fmac_f32_e32 v126, v48, v48
	v_fmac_f32_e32 v127, v50, v50
	v_add_f32_e32 v56, v61, v63
	v_add_f32_e32 v57, v57, v59
	v_add_f32_e32 v58, v124, v125
	v_add_f32_e32 v59, v126, v127
	v_add_f32_e32 v56, v56, v57
	v_add_f32_e32 v57, v58, v59
	v_add_f32_e32 v56, v56, v57
	ds_bpermute_b32 v57, v212, v56
	global_store_dwordx4 v[140:141], v[120:123], off
	global_store_dwordx4 v[138:139], v[52:55], off offset:512
	global_store_dwordx4 v[138:139], v[48:51], off offset:528
	s_nop 0
	v_cvt_pk_bf16_f32 v52, v52, v53
	v_cvt_pk_bf16_f32 v53, v54, v55
	v_cvt_pk_bf16_f32 v54, v48, v49
	s_waitcnt lgkmcnt(0)
	v_add_f32_e32 v48, v56, v57
	ds_bpermute_b32 v49, v211, v48
	v_cvt_pk_bf16_f32 v55, v50, v51
	v_lshl_add_u64 v[50:51], s[38:39], 0, v[136:137]
	global_store_dwordx4 v[50:51], v[52:55], off
	s_and_saveexec_b64 s[48:49], vcc
	s_cbranch_execz .LBB0_312
	v_lshlrev_b64 v[50:51], 6, v[118:119]
	v_lshl_add_u64 v[50:51], s[44:45], 0, v[50:51]
	v_lshl_add_u64 v[50:51], s[46:47], 2, v[50:51]
	s_lshl_b32 s14, s57, 2
	v_lshl_add_u64 v[50:51], v[50:51], 0, s[14:15]
	s_waitcnt lgkmcnt(0)
	v_add_f32_e32 v48, v48, v49
	global_store_dword v[50:51], v48, off
